# adds: in the GLA input-projection GEMM the padded gate tile (only 32 useful columns) skips the MFMAs of the unused column half and of the three unused wave columns (scalar branches around the MFMA gro
# speedup vs baseline: 1.0019x; 1.0019x over previous
; #define PG8_STAGE(bufoff, gbase, voff) do { _Pragma("unroll") for (int _i = 0; _i < 2; ++_i) \
;         __builtin_amdgcn_global_load_lds((const unsigned*)((const char*)(gbase) + (voff)[_i]), (LAS unsigned*)(lds + (bufoff) + ldsw + _i * 8192), 16, 0, 0); } while (0)
; #define PG8_LDA(dst, b, h) do { _Pragma("unroll") for (int m = 0; m < 4; ++m) _Pragma("unroll") for (int k = 0; k < 2; ++k) dst[m][k] = *(const LAS bf16x8*)(lds + PG8_SA(b, h) + aoff + m * 2048 + k * 1024); } while (0)
; #define PG8_LDB(dst, b, h) do { _Pragma("unroll") for (int n = 0; n < 2; ++n) _Pragma("unroll") for (int k = 0; k < 2; ++k) dst[n][k] = *(const LAS bf16x8*)(lds + PG8_SB(b, h) + boff + n * 2048 + k * 1024); } while (0)
;     __device__ __forceinline__ void operator()(const f32x4 (&acc)[2][2][4][2], const Unit& u, int wr, int wc, int fr, int fq, LAS unsigned char* lds, int tid, State& st) const {
;     ...
;                     if (u.pn != 12) *(u32x4*)(P + (size_t)row * GINP + col0 + bj * HALF) = w;
;                     if (bj == 0 && gate) { float* gp = gbuf + (size_t)row * 32 + 8 * fq; *(f32x4*)gp = v0; *(f32x4*)(gp + 4) = v1; }
; template <class Epi, class Sched>
; __device__ __forceinline__ void gemm_phase(LAS unsigned char* lds, const Gemm g, const Sched& S, const Epi& E) {
;     ...
;         const bool has_next = S.next(ui + 1, nxt);
;         const char* nA = has_next ? (const char*)g.A + (size_t)nxt.pm * tstepA + (size_t)nxt.pn * apn : cA; const char* nB = has_next ? (const char*)g.Bt + (size_t)nxt.pn * tstepB : cB;
;         for (int t = 0; t < nt; t += 2) {
;             const bool last = (t == nt - 2);
;             const char* a1 = cA + (size_t)(t + 1) * kstep;
;             const char* a2 = last ? nA : cA + (size_t)(t + 2) * kstep; const char* b2 = last ? nB : cB + (size_t)(t + 2) * kstep;
;             const char* a3 = a2 + kstep; const char* b3 = b2 + kstep;
;             PG8_LDB(B0, 0, 0); PG8_LDB(B1, 0, 1); PG8_SCHED; PG8_LDA(At, 0, 0); PG8_STAGE(PG8_SA(1, 1), a1 + hstepA, voffA);
;             PG8_WAIT_V(8); PG8_WAIT_L(0); PG8_BAR; PG8_MMA(0, 0, At, B0); PG8_MMA(0, 1, At, B1); PG8_BAR; PG8_SCHED;
;             PG8_LDA(At, 0, 1); PG8_STAGE(PG8_SB(0, 0), b2, voffB); PG8_STAGE(PG8_SB(0, 1), b2 + hstepB, voffB); PG8_STAGE(PG8_SA(0, 0), a2, voffA);
;             PG8_WAIT_V(8); PG8_WAIT_L(0); PG8_BAR; PG8_MMA(1, 0, At, B0); PG8_MMA(1, 1, At, B1); PG8_BAR; PG8_SCHED;
.LBB0_95:
	s_ashr_i32 s13, s12, 31
	s_lshl_b64 s[6:7], s[12:13], 19
	s_add_u32 s46, s84, s6
	s_addc_u32 s47, s85, s7
	s_and_b64 s[6:7], s[50:51], exec
	s_cselect_b32 s13, s47, s43
	s_cselect_b32 s57, s46, s42
	s_ashr_i32 s45, s44, 31
	s_lshl_b64 s[6:7], s[44:45], 19
	s_add_u32 s48, s8, s6
	s_addc_u32 s49, s9, s7
	s_and_b64 s[6:7], s[50:51], exec
	s_cselect_b32 s45, s49, s53
	s_cselect_b32 s68, s48, s52
	s_add_u32 s42, s42, 0x40080
	s_addc_u32 s43, s43, 0
	s_add_u32 s52, s52, 0x100
	s_addc_u32 s53, s53, 0
	s_mov_b32 s69, -2
	s_cmp_eq_u32 s40, 12
	s_cselect_b32 s101, 1, 0
	s_cmp_eq_u64 s[22:23], 0
	s_cselect_b32 s100, s101, 0
	s_add_u32 s0, s42, 0xfffc0080
	s_addc_u32 s6, s43, -1
	s_add_i32 s26, 0, 0x10000
	s_cmp_eq_u32 s69, 12
	s_cselect_b32 s15, s13, s6
	s_cselect_b32 s14, s57, s0
	v_add_u32_e32 v152, s26, v156
	s_cselect_b32 s7, s45, s53
	s_cselect_b32 s6, s68, s52
	s_add_i32 s0, 0, 0x14000
	ds_read_b128 v[144:147], v152
	ds_read_b128 v[148:151], v152 offset:1024
	ds_read_b128 v[164:167], v152 offset:2048
	ds_read_b128 v[168:171], v152 offset:3072
	v_add_u32_e32 v152, s0, v156
	ds_read_b128 v[172:175], v152
	ds_read_b128 v[190:193], v152 offset:1024
	ds_read_b128 v[196:199], v152 offset:2048
	ds_read_b128 v[200:203], v152 offset:3072
	v_lshl_add_u64 v[152:153], s[42:43], 0, v[140:141]
	s_add_i32 m0, s21, 0xc000
	ds_read_b128 v[204:207], v162
	ds_read_b128 v[208:211], v162 offset:1024
	ds_read_b128 v[212:215], v162 offset:2048
	ds_read_b128 v[216:219], v162 offset:3072
	ds_read_b128 v[220:223], v162 offset:4096
	ds_read_b128 v[224:227], v162 offset:5120
	ds_read_b128 v[228:231], v162 offset:6144
	ds_read_b128 v[232:235], v162 offset:7168
	global_load_lds_dwordx4 v[152:153], off
	v_lshl_add_u64 v[152:153], s[42:43], 0, v[142:143]
	s_add_i32 m0, s21, 0xe000
	s_nop 0
	global_load_lds_dwordx4 v[152:153], off
	s_cmp_lg_u32 s101, 0
	s_waitcnt vmcnt(8)
	s_waitcnt lgkmcnt(0)
	s_barrier
	s_waitcnt lgkmcnt(0)
	s_cbranch_scc1 .Lgt_p_0
	v_mfma_f32_16x16x32_bf16 v[128:131], v[144:147], v[204:207], 0
	v_mfma_f32_16x16x32_bf16 v[124:127], v[164:167], v[204:207], 0
	v_mfma_f32_16x16x32_bf16 v[120:123], v[144:147], v[212:215], 0
	v_mfma_f32_16x16x32_bf16 v[108:111], v[164:167], v[212:215], 0
	v_mfma_f32_16x16x32_bf16 v[104:107], v[144:147], v[220:223], 0
	v_mfma_f32_16x16x32_bf16 v[92:95], v[164:167], v[220:223], 0
	v_mfma_f32_16x16x32_bf16 v[88:91], v[144:147], v[228:231], 0
	v_mfma_f32_16x16x32_bf16 v[76:79], v[164:167], v[228:231], 0
	v_mfma_f32_16x16x32_bf16 v[128:131], v[148:151], v[208:211], v[128:131]
	v_mfma_f32_16x16x32_bf16 v[124:127], v[168:171], v[208:211], v[124:127]
	v_mfma_f32_16x16x32_bf16 v[120:123], v[148:151], v[216:219], v[120:123]
	v_mfma_f32_16x16x32_bf16 v[108:111], v[168:171], v[216:219], v[108:111]
	v_mfma_f32_16x16x32_bf16 v[104:107], v[148:151], v[224:227], v[104:107]
	v_mfma_f32_16x16x32_bf16 v[92:95], v[168:171], v[224:227], v[92:95]
	v_mfma_f32_16x16x32_bf16 v[88:91], v[148:151], v[232:235], v[88:91]
	v_mfma_f32_16x16x32_bf16 v[76:79], v[168:171], v[232:235], v[76:79]
	v_mfma_f32_16x16x32_bf16 v[116:119], v[172:175], v[204:207], 0
	v_mfma_f32_16x16x32_bf16 v[112:115], v[196:199], v[204:207], 0
	v_mfma_f32_16x16x32_bf16 v[100:103], v[172:175], v[212:215], 0
	v_mfma_f32_16x16x32_bf16 v[96:99], v[196:199], v[212:215], 0
	v_mfma_f32_16x16x32_bf16 v[84:87], v[172:175], v[220:223], 0
	v_mfma_f32_16x16x32_bf16 v[80:83], v[196:199], v[220:223], 0
	v_mfma_f32_16x16x32_bf16 v[72:75], v[172:175], v[228:231], 0
	v_mfma_f32_16x16x32_bf16 v[68:71], v[196:199], v[228:231], 0
	v_mfma_f32_16x16x32_bf16 v[116:119], v[190:193], v[208:211], v[116:119]
	v_mfma_f32_16x16x32_bf16 v[112:115], v[200:203], v[208:211], v[112:115]
	v_mfma_f32_16x16x32_bf16 v[100:103], v[190:193], v[216:219], v[100:103]
	v_mfma_f32_16x16x32_bf16 v[96:99], v[200:203], v[216:219], v[96:99]
	v_mfma_f32_16x16x32_bf16 v[84:87], v[190:193], v[224:227], v[84:87]
	v_mfma_f32_16x16x32_bf16 v[80:83], v[200:203], v[224:227], v[80:83]
	v_mfma_f32_16x16x32_bf16 v[72:75], v[190:193], v[232:235], v[72:75]
	v_mfma_f32_16x16x32_bf16 v[68:71], v[200:203], v[232:235], v[68:71]
.Lgt_p_0_done:
	s_barrier
	s_add_i32 s26, s26, s20
	v_lshl_add_u64 v[152:153], s[6:7], 0, v[160:161]
	s_mov_b32 m0, s26
	ds_read_b128 v[204:207], v162 offset:16384
	ds_read_b128 v[208:211], v162 offset:17408
	ds_read_b128 v[212:215], v162 offset:18432
	ds_read_b128 v[216:219], v162 offset:19456
	ds_read_b128 v[220:223], v162 offset:20480
	ds_read_b128 v[224:227], v162 offset:21504
	ds_read_b128 v[228:231], v162 offset:22528
	ds_read_b128 v[232:235], v162 offset:23552
	global_load_lds_dwordx4 v[152:153], off
	s_add_i32 m0, s26, 0x2000
	s_add_u32 s78, s6, 0x40000
	v_lshl_add_u64 v[176:177], s[6:7], 0, v[136:137]
	s_addc_u32 s79, s7, 0
	s_add_i32 s0, s0, s20
	global_load_lds_dwordx4 v[176:177], off
	v_lshl_add_u64 v[236:237], s[78:79], 0, v[160:161]
	s_mov_b32 m0, s0
	v_lshl_add_u64 v[238:239], s[14:15], 0, v[134:135]
	global_load_lds_dwordx4 v[236:237], off
	v_lshl_add_u64 v[236:237], s[78:79], 0, v[136:137]
	s_add_i32 m0, s0, 0x2000
	s_nop 0
	global_load_lds_dwordx4 v[236:237], off
	v_lshl_add_u64 v[236:237], s[14:15], 0, v[132:133]
	s_mov_b32 m0, s21
	s_nop 0
	global_load_lds_dwordx4 v[236:237], off
	s_mov_b32 m0, s24
	s_nop 0
	global_load_lds_dwordx4 v[238:239], off
	s_cmp_lg_u32 s101, 0
	s_waitcnt vmcnt(8)
	s_waitcnt lgkmcnt(0)
	s_barrier
	s_waitcnt lgkmcnt(0)
	s_cbranch_scc1 .Lgt_p_1
; #define PG8_STAGE(bufoff, gbase, voff) do { _Pragma("unroll") for (int _i = 0; _i < 2; ++_i) \
;         __builtin_amdgcn_global_load_lds((const unsigned*)((const char*)(gbase) + (voff)[_i]), (LAS unsigned*)(lds + (bufoff) + ldsw + _i * 8192), 16, 0, 0); } while (0)
; #define PG8_LDA(dst, b, h) do { _Pragma("unroll") for (int m = 0; m < 4; ++m) _Pragma("unroll") for (int k = 0; k < 2; ++k) dst[m][k] = *(const LAS bf16x8*)(lds + PG8_SA(b, h) + aoff + m * 2048 + k * 1024); } while (0)
; #define PG8_LDB(dst, b, h) do { _Pragma("unroll") for (int n = 0; n < 2; ++n) _Pragma("unroll") for (int k = 0; k < 2; ++k) dst[n][k] = *(const LAS bf16x8*)(lds + PG8_SB(b, h) + boff + n * 2048 + k * 1024); } while (0)
; #define PG8_MMA(ai, bj, At, Bt) do { __builtin_amdgcn_s_setprio(1); _Pragma("unroll") for (int m = 0; m < 4; ++m) _Pragma("unroll") for (int n = 0; n < 2; ++n) _Pragma("unroll") for (int k = 0; k < 2; ++k) \
;         acc[ai][bj][m][n] = __builtin_amdgcn_mfma_f32_16x16x32_bf16(Bt[n][k], At[m][k], acc[ai][bj][m][n], 0, 0, 0); __builtin_amdgcn_s_setprio(0); } while (0)
; #define PG8_WAIT_V(n) asm volatile("s_waitcnt vmcnt(" #n ")" ::: "memory")
; #define PG8_WAIT_L(n) asm volatile("s_waitcnt lgkmcnt(" #n ")" ::: "memory")
; #define PG8_BAR __builtin_amdgcn_s_barrier()
; #define PG8_SCHED __builtin_amdgcn_sched_barrier(0)
; template <class Epi, class Sched>
; __device__ __forceinline__ void gemm_phase(LAS unsigned char* lds, const Gemm g, const Sched& S, const Epi& E) {
;     ...
;             PG8_WAIT_V(8); PG8_WAIT_L(0); PG8_BAR; PG8_MMA(1, 0, At, B0); PG8_MMA(1, 1, At, B1); PG8_BAR; PG8_SCHED;
;             PG8_LDB(B0, 1, 0); PG8_LDB(B1, 1, 1); PG8_SCHED; PG8_LDA(At, 1, 0); PG8_STAGE(PG8_SA(0, 1), a2 + hstepA, voffA);
;             PG8_WAIT_V(8); PG8_WAIT_L(0); PG8_BAR; PG8_MMA(0, 0, At, B0); PG8_MMA(0, 1, At, B1); PG8_BAR; PG8_SCHED;
	v_mfma_f32_16x16x32_bf16 v[64:67], v[144:147], v[204:207], 0
	v_mfma_f32_16x16x32_bf16 v[60:63], v[164:167], v[204:207], 0
	v_mfma_f32_16x16x32_bf16 v[56:59], v[144:147], v[212:215], 0
	v_mfma_f32_16x16x32_bf16 v[44:47], v[164:167], v[212:215], 0
	v_mfma_f32_16x16x32_bf16 v[40:43], v[144:147], v[220:223], 0
	v_mfma_f32_16x16x32_bf16 v[28:31], v[164:167], v[220:223], 0
	v_mfma_f32_16x16x32_bf16 v[24:27], v[144:147], v[228:231], 0
	v_mfma_f32_16x16x32_bf16 v[12:15], v[164:167], v[228:231], 0
	v_mfma_f32_16x16x32_bf16 v[64:67], v[148:151], v[208:211], v[64:67]
	v_mfma_f32_16x16x32_bf16 v[60:63], v[168:171], v[208:211], v[60:63]
	v_mfma_f32_16x16x32_bf16 v[56:59], v[148:151], v[216:219], v[56:59]
	v_mfma_f32_16x16x32_bf16 v[44:47], v[168:171], v[216:219], v[44:47]
	v_mfma_f32_16x16x32_bf16 v[40:43], v[148:151], v[224:227], v[40:43]
	v_mfma_f32_16x16x32_bf16 v[28:31], v[168:171], v[224:227], v[28:31]
	v_mfma_f32_16x16x32_bf16 v[24:27], v[148:151], v[232:235], v[24:27]
	v_mfma_f32_16x16x32_bf16 v[12:15], v[168:171], v[232:235], v[12:15]
	v_mfma_f32_16x16x32_bf16 v[52:55], v[172:175], v[204:207], 0
	v_mfma_f32_16x16x32_bf16 v[48:51], v[196:199], v[204:207], 0
	v_mfma_f32_16x16x32_bf16 v[36:39], v[172:175], v[212:215], 0
	v_mfma_f32_16x16x32_bf16 v[32:35], v[196:199], v[212:215], 0
	v_mfma_f32_16x16x32_bf16 v[20:23], v[172:175], v[220:223], 0
	v_mfma_f32_16x16x32_bf16 v[16:19], v[196:199], v[220:223], 0
	v_mfma_f32_16x16x32_bf16 v[8:11], v[172:175], v[228:231], 0
	v_mfma_f32_16x16x32_bf16 v[4:7], v[196:199], v[228:231], 0
	v_mfma_f32_16x16x32_bf16 v[52:55], v[190:193], v[208:211], v[52:55]
	v_mfma_f32_16x16x32_bf16 v[48:51], v[200:203], v[208:211], v[48:51]
	v_mfma_f32_16x16x32_bf16 v[36:39], v[190:193], v[216:219], v[36:39]
	v_mfma_f32_16x16x32_bf16 v[32:35], v[200:203], v[216:219], v[32:35]
	v_mfma_f32_16x16x32_bf16 v[20:23], v[190:193], v[224:227], v[20:23]
	v_mfma_f32_16x16x32_bf16 v[16:19], v[200:203], v[224:227], v[16:19]
	v_mfma_f32_16x16x32_bf16 v[8:11], v[190:193], v[232:235], v[8:11]
	v_mfma_f32_16x16x32_bf16 v[4:7], v[200:203], v[232:235], v[4:7]
.Lgt_p_1_done:
	s_barrier
	s_add_i32 s0, 0, 0x18000
	v_add_u32_e32 v163, s0, v156
	s_add_i32 s26, 0, 0x1c000
	ds_read_b128 v[144:147], v163
	ds_read_b128 v[148:151], v163 offset:1024
	ds_read_b128 v[164:167], v163 offset:2048
	ds_read_b128 v[168:171], v163 offset:3072
	v_add_u32_e32 v163, s26, v156
	ds_read_b128 v[172:175], v163
	ds_read_b128 v[190:193], v163 offset:1024
	ds_read_b128 v[196:199], v163 offset:2048
	ds_read_b128 v[200:203], v163 offset:3072
	s_add_u32 s14, s14, 0x40000
	s_addc_u32 s15, s15, 0
	s_mov_b32 m0, s25
	v_lshl_add_u64 v[240:241], s[14:15], 0, v[132:133]
	ds_read_b128 v[204:207], v162 offset:32768
	ds_read_b128 v[208:211], v162 offset:33792
	ds_read_b128 v[212:215], v162 offset:34816
	ds_read_b128 v[216:219], v162 offset:35840
	ds_read_b128 v[220:223], v162 offset:36864
	ds_read_b128 v[224:227], v162 offset:37888
	ds_read_b128 v[228:231], v162 offset:38912
	ds_read_b128 v[232:235], v162 offset:39936
	global_load_lds_dwordx4 v[240:241], off
	v_lshl_add_u64 v[240:241], s[14:15], 0, v[134:135]
	s_mov_b32 m0, s28
	s_nop 0
	global_load_lds_dwordx4 v[240:241], off
	s_cmp_lg_u32 s101, 0
	s_waitcnt vmcnt(8)
	s_waitcnt lgkmcnt(0)
	s_barrier
	s_waitcnt lgkmcnt(0)
	s_cbranch_scc1 .Lgt_p_2
	v_mfma_f32_16x16x32_bf16 v[128:131], v[144:147], v[204:207], v[128:131]
	v_mfma_f32_16x16x32_bf16 v[124:127], v[164:167], v[204:207], v[124:127]
	v_mfma_f32_16x16x32_bf16 v[120:123], v[144:147], v[212:215], v[120:123]
	v_mfma_f32_16x16x32_bf16 v[108:111], v[164:167], v[212:215], v[108:111]
	v_mfma_f32_16x16x32_bf16 v[104:107], v[144:147], v[220:223], v[104:107]
	v_mfma_f32_16x16x32_bf16 v[92:95], v[164:167], v[220:223], v[92:95]
	v_mfma_f32_16x16x32_bf16 v[88:91], v[144:147], v[228:231], v[88:91]
	v_mfma_f32_16x16x32_bf16 v[76:79], v[164:167], v[228:231], v[76:79]
	v_mfma_f32_16x16x32_bf16 v[128:131], v[148:151], v[208:211], v[128:131]
	v_mfma_f32_16x16x32_bf16 v[124:127], v[168:171], v[208:211], v[124:127]
	v_mfma_f32_16x16x32_bf16 v[120:123], v[148:151], v[216:219], v[120:123]
	v_mfma_f32_16x16x32_bf16 v[108:111], v[168:171], v[216:219], v[108:111]
	v_mfma_f32_16x16x32_bf16 v[104:107], v[148:151], v[224:227], v[104:107]
	v_mfma_f32_16x16x32_bf16 v[92:95], v[168:171], v[224:227], v[92:95]
	v_mfma_f32_16x16x32_bf16 v[88:91], v[148:151], v[232:235], v[88:91]
	v_mfma_f32_16x16x32_bf16 v[76:79], v[168:171], v[232:235], v[76:79]
	v_mfma_f32_16x16x32_bf16 v[116:119], v[172:175], v[204:207], v[116:119]
	v_mfma_f32_16x16x32_bf16 v[112:115], v[196:199], v[204:207], v[112:115]
	v_mfma_f32_16x16x32_bf16 v[100:103], v[172:175], v[212:215], v[100:103]
	v_mfma_f32_16x16x32_bf16 v[96:99], v[196:199], v[212:215], v[96:99]
	v_mfma_f32_16x16x32_bf16 v[84:87], v[172:175], v[220:223], v[84:87]
	v_mfma_f32_16x16x32_bf16 v[80:83], v[196:199], v[220:223], v[80:83]
	v_mfma_f32_16x16x32_bf16 v[72:75], v[172:175], v[228:231], v[72:75]
	v_mfma_f32_16x16x32_bf16 v[68:71], v[196:199], v[228:231], v[68:71]
	v_mfma_f32_16x16x32_bf16 v[116:119], v[190:193], v[208:211], v[116:119]
	v_mfma_f32_16x16x32_bf16 v[112:115], v[200:203], v[208:211], v[112:115]
	v_mfma_f32_16x16x32_bf16 v[100:103], v[190:193], v[216:219], v[100:103]
	v_mfma_f32_16x16x32_bf16 v[96:99], v[200:203], v[216:219], v[96:99]
	v_mfma_f32_16x16x32_bf16 v[84:87], v[190:193], v[224:227], v[84:87]
	v_mfma_f32_16x16x32_bf16 v[80:83], v[200:203], v[224:227], v[80:83]
	v_mfma_f32_16x16x32_bf16 v[72:75], v[190:193], v[232:235], v[72:75]
	v_mfma_f32_16x16x32_bf16 v[68:71], v[200:203], v[232:235], v[68:71]
; #define PG8_STAGE(bufoff, gbase, voff) do { _Pragma("unroll") for (int _i = 0; _i < 2; ++_i) \
;         __builtin_amdgcn_global_load_lds((const unsigned*)((const char*)(gbase) + (voff)[_i]), (LAS unsigned*)(lds + (bufoff) + ldsw + _i * 8192), 16, 0, 0); } while (0)
; #define PG8_LDA(dst, b, h) do { _Pragma("unroll") for (int m = 0; m < 4; ++m) _Pragma("unroll") for (int k = 0; k < 2; ++k) dst[m][k] = *(const LAS bf16x8*)(lds + PG8_SA(b, h) + aoff + m * 2048 + k * 1024); } while (0)
; #define PG8_LDB(dst, b, h) do { _Pragma("unroll") for (int n = 0; n < 2; ++n) _Pragma("unroll") for (int k = 0; k < 2; ++k) dst[n][k] = *(const LAS bf16x8*)(lds + PG8_SB(b, h) + boff + n * 2048 + k * 1024); } while (0)
; #define PG8_MMA(ai, bj, At, Bt) do { __builtin_amdgcn_s_setprio(1); _Pragma("unroll") for (int m = 0; m < 4; ++m) _Pragma("unroll") for (int n = 0; n < 2; ++n) _Pragma("unroll") for (int k = 0; k < 2; ++k) \
;         acc[ai][bj][m][n] = __builtin_amdgcn_mfma_f32_16x16x32_bf16(Bt[n][k], At[m][k], acc[ai][bj][m][n], 0, 0, 0); __builtin_amdgcn_s_setprio(0); } while (0)
; template <class Epi, class Sched>
; __device__ __forceinline__ void gemm_phase(LAS unsigned char* lds, const Gemm g, const Sched& S, const Epi& E) {
;     ...
;         const bool has_next = S.next(ui + 1, nxt);
;         const char* nA = has_next ? (const char*)g.A + (size_t)nxt.pm * tstepA + (size_t)nxt.pn * apn : cA; const char* nB = has_next ? (const char*)g.Bt + (size_t)nxt.pn * tstepB : cB;
;         for (int t = 0; t < nt; t += 2) {
;             const bool last = (t == nt - 2);
;             const char* a1 = cA + (size_t)(t + 1) * kstep;
;             const char* a2 = last ? nA : cA + (size_t)(t + 2) * kstep; const char* b2 = last ? nB : cB + (size_t)(t + 2) * kstep;
;             const char* a3 = a2 + kstep; const char* b3 = b2 + kstep;
;             PG8_LDB(B0, 0, 0); PG8_LDB(B1, 0, 1); PG8_SCHED; PG8_LDA(At, 0, 0); PG8_STAGE(PG8_SA(1, 1), a1 + hstepA, voffA);
;             PG8_WAIT_V(8); PG8_WAIT_L(0); PG8_BAR; PG8_MMA(0, 0, At, B0); PG8_MMA(0, 1, At, B1); PG8_BAR; PG8_SCHED;
;     ...
;             PG8_LDA(At, 1, 1); PG8_STAGE(PG8_SB(1, 0), b3, voffB); PG8_STAGE(PG8_SB(1, 1), b3 + hstepB, voffB); PG8_STAGE(PG8_SA(1, 0), a3, voffA);
;             PG8_WAIT_V(8); PG8_WAIT_L(0); PG8_BAR; PG8_MMA(1, 0, At, B0); PG8_MMA(1, 1, At, B1); PG8_BAR; PG8_SCHED;
;         }
.Lgt_p_2_done:
	s_barrier
	s_add_i32 s0, s0, s20
	v_lshl_add_u64 v[152:153], v[152:153], 0, s[30:31]
	s_mov_b32 m0, s0
	ds_read_b128 v[204:207], v162 offset:49152
	ds_read_b128 v[208:211], v162 offset:50176
	ds_read_b128 v[212:215], v162 offset:51200
	ds_read_b128 v[216:219], v162 offset:52224
	ds_read_b128 v[220:223], v162 offset:53248
	ds_read_b128 v[224:227], v162 offset:54272
	ds_read_b128 v[228:231], v162 offset:55296
	ds_read_b128 v[232:235], v162 offset:56320
	global_load_lds_dwordx4 v[152:153], off
	s_add_i32 m0, s0, 0x2000
	s_add_u32 s6, s6, 0x40080
	v_lshl_add_u64 v[152:153], v[176:177], 0, s[30:31]
	s_addc_u32 s7, s7, 0
	s_add_i32 s0, s26, s20
	global_load_lds_dwordx4 v[152:153], off
	v_lshl_add_u64 v[152:153], s[6:7], 0, v[160:161]
	s_mov_b32 m0, s0
	s_nop 0
	global_load_lds_dwordx4 v[152:153], off
	v_lshl_add_u64 v[152:153], s[6:7], 0, v[136:137]
	s_add_i32 m0, s0, 0x2000
	s_nop 0
	global_load_lds_dwordx4 v[152:153], off
	v_lshl_add_u64 v[152:153], v[236:237], 0, s[30:31]
	s_mov_b32 m0, s33
	s_nop 0
	global_load_lds_dwordx4 v[152:153], off
	v_lshl_add_u64 v[152:153], v[238:239], 0, s[30:31]
	s_mov_b32 m0, s54
	s_nop 0
	global_load_lds_dwordx4 v[152:153], off
	s_cmp_lg_u32 s101, 0
	s_waitcnt vmcnt(8)
	s_waitcnt lgkmcnt(0)
	s_barrier
	s_waitcnt lgkmcnt(0)
	s_cbranch_scc1 .Lgt_p_3
	v_mfma_f32_16x16x32_bf16 v[64:67], v[144:147], v[204:207], v[64:67]
	v_mfma_f32_16x16x32_bf16 v[60:63], v[164:167], v[204:207], v[60:63]
	v_mfma_f32_16x16x32_bf16 v[56:59], v[144:147], v[212:215], v[56:59]
	v_mfma_f32_16x16x32_bf16 v[44:47], v[164:167], v[212:215], v[44:47]
	v_mfma_f32_16x16x32_bf16 v[40:43], v[144:147], v[220:223], v[40:43]
	v_mfma_f32_16x16x32_bf16 v[28:31], v[164:167], v[220:223], v[28:31]
	v_mfma_f32_16x16x32_bf16 v[24:27], v[144:147], v[228:231], v[24:27]
	v_mfma_f32_16x16x32_bf16 v[12:15], v[164:167], v[228:231], v[12:15]
	v_mfma_f32_16x16x32_bf16 v[64:67], v[148:151], v[208:211], v[64:67]
	v_mfma_f32_16x16x32_bf16 v[60:63], v[168:171], v[208:211], v[60:63]
	v_mfma_f32_16x16x32_bf16 v[56:59], v[148:151], v[216:219], v[56:59]
	v_mfma_f32_16x16x32_bf16 v[44:47], v[168:171], v[216:219], v[44:47]
	v_mfma_f32_16x16x32_bf16 v[40:43], v[148:151], v[224:227], v[40:43]
	v_mfma_f32_16x16x32_bf16 v[28:31], v[168:171], v[224:227], v[28:31]
	v_mfma_f32_16x16x32_bf16 v[24:27], v[148:151], v[232:235], v[24:27]
	v_mfma_f32_16x16x32_bf16 v[12:15], v[168:171], v[232:235], v[12:15]
	v_mfma_f32_16x16x32_bf16 v[52:55], v[172:175], v[204:207], v[52:55]
	v_mfma_f32_16x16x32_bf16 v[48:51], v[196:199], v[204:207], v[48:51]
	v_mfma_f32_16x16x32_bf16 v[36:39], v[172:175], v[212:215], v[36:39]
	v_mfma_f32_16x16x32_bf16 v[32:35], v[196:199], v[212:215], v[32:35]
	v_mfma_f32_16x16x32_bf16 v[20:23], v[172:175], v[220:223], v[20:23]
	v_mfma_f32_16x16x32_bf16 v[16:19], v[196:199], v[220:223], v[16:19]
	v_mfma_f32_16x16x32_bf16 v[8:11], v[172:175], v[228:231], v[8:11]
	v_mfma_f32_16x16x32_bf16 v[4:7], v[196:199], v[228:231], v[4:7]
	v_mfma_f32_16x16x32_bf16 v[52:55], v[190:193], v[208:211], v[52:55]
	v_mfma_f32_16x16x32_bf16 v[48:51], v[200:203], v[208:211], v[48:51]
	v_mfma_f32_16x16x32_bf16 v[36:39], v[190:193], v[216:219], v[36:39]
	v_mfma_f32_16x16x32_bf16 v[32:35], v[200:203], v[216:219], v[32:35]
	v_mfma_f32_16x16x32_bf16 v[20:23], v[190:193], v[224:227], v[20:23]
	v_mfma_f32_16x16x32_bf16 v[16:19], v[200:203], v[224:227], v[16:19]
	v_mfma_f32_16x16x32_bf16 v[8:11], v[190:193], v[232:235], v[8:11]
	v_mfma_f32_16x16x32_bf16 v[4:7], v[200:203], v[232:235], v[4:7]
.Lgt_p_3_done:
	s_barrier
	s_add_i32 s69, s69, 2
	s_add_u32 s42, s42, 0x100
	s_addc_u32 s43, s43, 0
	s_add_u32 s52, s52, 0x100
	s_addc_u32 s53, s53, 0
	s_cmp_gt_u32 s69, 13
.LBB0_96:
	s_add_u32 s0, s42, 0xfffc0080
	s_addc_u32 s6, s43, -1
	s_add_i32 s26, 0, 0x10000
	s_cmp_eq_u32 s69, 12
	s_cselect_b32 s15, s13, s6
	s_cselect_b32 s14, s57, s0
	v_add_u32_e32 v152, s26, v156
	s_cselect_b32 s7, s45, s53
	s_cselect_b32 s6, s68, s52
	s_add_i32 s0, 0, 0x14000
	ds_read_b128 v[144:147], v152
	ds_read_b128 v[148:151], v152 offset:1024
	ds_read_b128 v[164:167], v152 offset:2048
	ds_read_b128 v[168:171], v152 offset:3072
	v_add_u32_e32 v152, s0, v156
	ds_read_b128 v[172:175], v152
	ds_read_b128 v[190:193], v152 offset:1024
	ds_read_b128 v[196:199], v152 offset:2048
	ds_read_b128 v[200:203], v152 offset:3072
	v_lshl_add_u64 v[152:153], s[42:43], 0, v[140:141]
	s_add_i32 m0, s21, 0xc000
	ds_read_b128 v[204:207], v162
	ds_read_b128 v[208:211], v162 offset:1024
	ds_read_b128 v[212:215], v162 offset:2048
	ds_read_b128 v[216:219], v162 offset:3072
	ds_read_b128 v[220:223], v162 offset:4096
	ds_read_b128 v[224:227], v162 offset:5120
	ds_read_b128 v[228:231], v162 offset:6144
	ds_read_b128 v[232:235], v162 offset:7168
	global_load_lds_dwordx4 v[152:153], off
	v_lshl_add_u64 v[152:153], s[42:43], 0, v[142:143]
	s_add_i32 m0, s21, 0xe000
	s_nop 0
	global_load_lds_dwordx4 v[152:153], off
	s_cmp_lg_u32 s101, 0
	s_waitcnt vmcnt(8)
	s_waitcnt lgkmcnt(0)
	s_barrier
	s_waitcnt lgkmcnt(0)
	s_cbranch_scc1 .Lgt_l_0
; #define PG8_STAGE(bufoff, gbase, voff) do { _Pragma("unroll") for (int _i = 0; _i < 2; ++_i) \
;         __builtin_amdgcn_global_load_lds((const unsigned*)((const char*)(gbase) + (voff)[_i]), (LAS unsigned*)(lds + (bufoff) + ldsw + _i * 8192), 16, 0, 0); } while (0)
; #define PG8_LDA(dst, b, h) do { _Pragma("unroll") for (int m = 0; m < 4; ++m) _Pragma("unroll") for (int k = 0; k < 2; ++k) dst[m][k] = *(const LAS bf16x8*)(lds + PG8_SA(b, h) + aoff + m * 2048 + k * 1024); } while (0)
; #define PG8_LDB(dst, b, h) do { _Pragma("unroll") for (int n = 0; n < 2; ++n) _Pragma("unroll") for (int k = 0; k < 2; ++k) dst[n][k] = *(const LAS bf16x8*)(lds + PG8_SB(b, h) + boff + n * 2048 + k * 1024); } while (0)
; #define PG8_MMA(ai, bj, At, Bt) do { __builtin_amdgcn_s_setprio(1); _Pragma("unroll") for (int m = 0; m < 4; ++m) _Pragma("unroll") for (int n = 0; n < 2; ++n) _Pragma("unroll") for (int k = 0; k < 2; ++k) \
;         acc[ai][bj][m][n] = __builtin_amdgcn_mfma_f32_16x16x32_bf16(Bt[n][k], At[m][k], acc[ai][bj][m][n], 0, 0, 0); __builtin_amdgcn_s_setprio(0); } while (0)
; #define PG8_WAIT_V(n) asm volatile("s_waitcnt vmcnt(" #n ")" ::: "memory")
; #define PG8_WAIT_L(n) asm volatile("s_waitcnt lgkmcnt(" #n ")" ::: "memory")
; #define PG8_BAR __builtin_amdgcn_s_barrier()
; #define PG8_SCHED __builtin_amdgcn_sched_barrier(0)
; template <class Epi, class Sched>
; __device__ __forceinline__ void gemm_phase(LAS unsigned char* lds, const Gemm g, const Sched& S, const Epi& E) {
;     ...
;             PG8_WAIT_V(8); PG8_WAIT_L(0); PG8_BAR; PG8_MMA(0, 0, At, B0); PG8_MMA(0, 1, At, B1); PG8_BAR; PG8_SCHED;
;             PG8_LDA(At, 0, 1); PG8_STAGE(PG8_SB(0, 0), b2, voffB); PG8_STAGE(PG8_SB(0, 1), b2 + hstepB, voffB); PG8_STAGE(PG8_SA(0, 0), a2, voffA);
;             PG8_WAIT_V(8); PG8_WAIT_L(0); PG8_BAR; PG8_MMA(1, 0, At, B0); PG8_MMA(1, 1, At, B1); PG8_BAR; PG8_SCHED;
;             PG8_LDB(B0, 1, 0); PG8_LDB(B1, 1, 1); PG8_SCHED; PG8_LDA(At, 1, 0); PG8_STAGE(PG8_SA(0, 1), a2 + hstepA, voffA);
;             PG8_WAIT_V(8); PG8_WAIT_L(0); PG8_BAR; PG8_MMA(0, 0, At, B0); PG8_MMA(0, 1, At, B1); PG8_BAR; PG8_SCHED;
	v_mfma_f32_16x16x32_bf16 v[128:131], v[144:147], v[204:207], v[128:131]
	v_mfma_f32_16x16x32_bf16 v[124:127], v[164:167], v[204:207], v[124:127]
	v_mfma_f32_16x16x32_bf16 v[120:123], v[144:147], v[212:215], v[120:123]
	v_mfma_f32_16x16x32_bf16 v[108:111], v[164:167], v[212:215], v[108:111]
	v_mfma_f32_16x16x32_bf16 v[104:107], v[144:147], v[220:223], v[104:107]
	v_mfma_f32_16x16x32_bf16 v[92:95], v[164:167], v[220:223], v[92:95]
	v_mfma_f32_16x16x32_bf16 v[88:91], v[144:147], v[228:231], v[88:91]
	v_mfma_f32_16x16x32_bf16 v[76:79], v[164:167], v[228:231], v[76:79]
	v_mfma_f32_16x16x32_bf16 v[128:131], v[148:151], v[208:211], v[128:131]
	v_mfma_f32_16x16x32_bf16 v[124:127], v[168:171], v[208:211], v[124:127]
	v_mfma_f32_16x16x32_bf16 v[120:123], v[148:151], v[216:219], v[120:123]
	v_mfma_f32_16x16x32_bf16 v[108:111], v[168:171], v[216:219], v[108:111]
	v_mfma_f32_16x16x32_bf16 v[104:107], v[148:151], v[224:227], v[104:107]
	v_mfma_f32_16x16x32_bf16 v[92:95], v[168:171], v[224:227], v[92:95]
	v_mfma_f32_16x16x32_bf16 v[88:91], v[148:151], v[232:235], v[88:91]
	v_mfma_f32_16x16x32_bf16 v[76:79], v[168:171], v[232:235], v[76:79]
	v_mfma_f32_16x16x32_bf16 v[116:119], v[172:175], v[204:207], v[116:119]
	v_mfma_f32_16x16x32_bf16 v[112:115], v[196:199], v[204:207], v[112:115]
	v_mfma_f32_16x16x32_bf16 v[100:103], v[172:175], v[212:215], v[100:103]
	v_mfma_f32_16x16x32_bf16 v[96:99], v[196:199], v[212:215], v[96:99]
	v_mfma_f32_16x16x32_bf16 v[84:87], v[172:175], v[220:223], v[84:87]
	v_mfma_f32_16x16x32_bf16 v[80:83], v[196:199], v[220:223], v[80:83]
	v_mfma_f32_16x16x32_bf16 v[72:75], v[172:175], v[228:231], v[72:75]
	v_mfma_f32_16x16x32_bf16 v[68:71], v[196:199], v[228:231], v[68:71]
	v_mfma_f32_16x16x32_bf16 v[116:119], v[190:193], v[208:211], v[116:119]
	v_mfma_f32_16x16x32_bf16 v[112:115], v[200:203], v[208:211], v[112:115]
	v_mfma_f32_16x16x32_bf16 v[100:103], v[190:193], v[216:219], v[100:103]
	v_mfma_f32_16x16x32_bf16 v[96:99], v[200:203], v[216:219], v[96:99]
	v_mfma_f32_16x16x32_bf16 v[84:87], v[190:193], v[224:227], v[84:87]
	v_mfma_f32_16x16x32_bf16 v[80:83], v[200:203], v[224:227], v[80:83]
	v_mfma_f32_16x16x32_bf16 v[72:75], v[190:193], v[232:235], v[72:75]
	v_mfma_f32_16x16x32_bf16 v[68:71], v[200:203], v[232:235], v[68:71]
.Lgt_l_0_done:
	s_barrier
	s_add_i32 s26, s26, s20
	v_lshl_add_u64 v[152:153], s[6:7], 0, v[160:161]
	s_mov_b32 m0, s26
	ds_read_b128 v[204:207], v162 offset:16384
	ds_read_b128 v[208:211], v162 offset:17408
	ds_read_b128 v[212:215], v162 offset:18432
	ds_read_b128 v[216:219], v162 offset:19456
	ds_read_b128 v[220:223], v162 offset:20480
	ds_read_b128 v[224:227], v162 offset:21504
	ds_read_b128 v[228:231], v162 offset:22528
	ds_read_b128 v[232:235], v162 offset:23552
	global_load_lds_dwordx4 v[152:153], off
	s_add_i32 m0, s26, 0x2000
	s_add_u32 s78, s6, 0x40000
	v_lshl_add_u64 v[176:177], s[6:7], 0, v[136:137]
	s_addc_u32 s79, s7, 0
	s_add_i32 s0, s0, s20
	global_load_lds_dwordx4 v[176:177], off
	v_lshl_add_u64 v[236:237], s[78:79], 0, v[160:161]
	s_mov_b32 m0, s0
	v_lshl_add_u64 v[238:239], s[14:15], 0, v[134:135]
	global_load_lds_dwordx4 v[236:237], off
	v_lshl_add_u64 v[236:237], s[78:79], 0, v[136:137]
	s_add_i32 m0, s0, 0x2000
	s_nop 0
	global_load_lds_dwordx4 v[236:237], off
	v_lshl_add_u64 v[236:237], s[14:15], 0, v[132:133]
	s_mov_b32 m0, s21
	s_nop 0
	global_load_lds_dwordx4 v[236:237], off
	s_mov_b32 m0, s24
	s_nop 0
	global_load_lds_dwordx4 v[238:239], off
	s_cmp_lg_u32 s101, 0
	s_waitcnt vmcnt(8)
	s_waitcnt lgkmcnt(0)
	s_barrier
	s_waitcnt lgkmcnt(0)
	s_cbranch_scc1 .Lgt_l_1
	v_mfma_f32_16x16x32_bf16 v[64:67], v[144:147], v[204:207], v[64:67]
	v_mfma_f32_16x16x32_bf16 v[60:63], v[164:167], v[204:207], v[60:63]
	v_mfma_f32_16x16x32_bf16 v[56:59], v[144:147], v[212:215], v[56:59]
	v_mfma_f32_16x16x32_bf16 v[44:47], v[164:167], v[212:215], v[44:47]
	v_mfma_f32_16x16x32_bf16 v[40:43], v[144:147], v[220:223], v[40:43]
	v_mfma_f32_16x16x32_bf16 v[28:31], v[164:167], v[220:223], v[28:31]
	v_mfma_f32_16x16x32_bf16 v[24:27], v[144:147], v[228:231], v[24:27]
	v_mfma_f32_16x16x32_bf16 v[12:15], v[164:167], v[228:231], v[12:15]
	v_mfma_f32_16x16x32_bf16 v[64:67], v[148:151], v[208:211], v[64:67]
	v_mfma_f32_16x16x32_bf16 v[60:63], v[168:171], v[208:211], v[60:63]
	v_mfma_f32_16x16x32_bf16 v[56:59], v[148:151], v[216:219], v[56:59]
	v_mfma_f32_16x16x32_bf16 v[44:47], v[168:171], v[216:219], v[44:47]
	v_mfma_f32_16x16x32_bf16 v[40:43], v[148:151], v[224:227], v[40:43]
	v_mfma_f32_16x16x32_bf16 v[28:31], v[168:171], v[224:227], v[28:31]
	v_mfma_f32_16x16x32_bf16 v[24:27], v[148:151], v[232:235], v[24:27]
	v_mfma_f32_16x16x32_bf16 v[12:15], v[168:171], v[232:235], v[12:15]
	v_mfma_f32_16x16x32_bf16 v[52:55], v[172:175], v[204:207], v[52:55]
	v_mfma_f32_16x16x32_bf16 v[48:51], v[196:199], v[204:207], v[48:51]
	v_mfma_f32_16x16x32_bf16 v[36:39], v[172:175], v[212:215], v[36:39]
	v_mfma_f32_16x16x32_bf16 v[32:35], v[196:199], v[212:215], v[32:35]
	v_mfma_f32_16x16x32_bf16 v[20:23], v[172:175], v[220:223], v[20:23]
	v_mfma_f32_16x16x32_bf16 v[16:19], v[196:199], v[220:223], v[16:19]
	v_mfma_f32_16x16x32_bf16 v[8:11], v[172:175], v[228:231], v[8:11]
	v_mfma_f32_16x16x32_bf16 v[4:7], v[196:199], v[228:231], v[4:7]
	v_mfma_f32_16x16x32_bf16 v[52:55], v[190:193], v[208:211], v[52:55]
	v_mfma_f32_16x16x32_bf16 v[48:51], v[200:203], v[208:211], v[48:51]
	v_mfma_f32_16x16x32_bf16 v[36:39], v[190:193], v[216:219], v[36:39]
	v_mfma_f32_16x16x32_bf16 v[32:35], v[200:203], v[216:219], v[32:35]
	v_mfma_f32_16x16x32_bf16 v[20:23], v[190:193], v[224:227], v[20:23]
	v_mfma_f32_16x16x32_bf16 v[16:19], v[200:203], v[224:227], v[16:19]
	v_mfma_f32_16x16x32_bf16 v[8:11], v[190:193], v[232:235], v[8:11]
	v_mfma_f32_16x16x32_bf16 v[4:7], v[200:203], v[232:235], v[4:7]

; #define PG8_STAGE(bufoff, gbase, voff) do { _Pragma("unroll") for (int _i = 0; _i < 2; ++_i) \
;         __builtin_amdgcn_global_load_lds((const unsigned*)((const char*)(gbase) + (voff)[_i]), (LAS unsigned*)(lds + (bufoff) + ldsw + _i * 8192), 16, 0, 0); } while (0)
; #define PG8_LDA(dst, b, h) do { _Pragma("unroll") for (int m = 0; m < 4; ++m) _Pragma("unroll") for (int k = 0; k < 2; ++k) dst[m][k] = *(const LAS bf16x8*)(lds + PG8_SA(b, h) + aoff + m * 2048 + k * 1024); } while (0)
; #define PG8_LDB(dst, b, h) do { _Pragma("unroll") for (int n = 0; n < 2; ++n) _Pragma("unroll") for (int k = 0; k < 2; ++k) dst[n][k] = *(const LAS bf16x8*)(lds + PG8_SB(b, h) + boff + n * 2048 + k * 1024); } while (0)
; #define PG8_WAIT_V(n) asm volatile("s_waitcnt vmcnt(" #n ")" ::: "memory")
; template <class Epi, class Sched>
; __device__ __forceinline__ void gemm_phase(LAS unsigned char* lds, const Gemm g, const Sched& S, const Epi& E) {
;     ...
;         for (int t = 0; t < nt; t += 2) {
;             const bool last = (t == nt - 2);
;             const char* a1 = cA + (size_t)(t + 1) * kstep;
;             const char* a2 = last ? nA : cA + (size_t)(t + 2) * kstep; const char* b2 = last ? nB : cB + (size_t)(t + 2) * kstep;
;             const char* a3 = a2 + kstep; const char* b3 = b2 + kstep;
;             PG8_LDB(B0, 0, 0); PG8_LDB(B1, 0, 1); PG8_SCHED; PG8_LDA(At, 0, 0); PG8_STAGE(PG8_SA(1, 1), a1 + hstepA, voffA);
;             PG8_WAIT_V(8); PG8_WAIT_L(0); PG8_BAR; PG8_MMA(0, 0, At, B0); PG8_MMA(0, 1, At, B1); PG8_BAR; PG8_SCHED;
;             PG8_LDA(At, 0, 1); PG8_STAGE(PG8_SB(0, 0), b2, voffB); PG8_STAGE(PG8_SB(0, 1), b2 + hstepB, voffB); PG8_STAGE(PG8_SA(0, 0), a2, voffA);
;             PG8_WAIT_V(8); PG8_WAIT_L(0); PG8_BAR; PG8_MMA(1, 0, At, B0); PG8_MMA(1, 1, At, B1); PG8_BAR; PG8_SCHED;
;             PG8_LDB(B0, 1, 0); PG8_LDB(B1, 1, 1); PG8_SCHED; PG8_LDA(At, 1, 0); PG8_STAGE(PG8_SA(0, 1), a2 + hstepA, voffA);
;             PG8_WAIT_V(8); PG8_WAIT_L(0); PG8_BAR; PG8_MMA(0, 0, At, B0); PG8_MMA(0, 1, At, B1); PG8_BAR; PG8_SCHED;
;             PG8_LDA(At, 1, 1); PG8_STAGE(PG8_SB(1, 0), b3, voffB); PG8_STAGE(PG8_SB(1, 1), b3 + hstepB, voffB); PG8_STAGE(PG8_SA(1, 0), a3, voffA);
;             PG8_WAIT_V(8); PG8_WAIT_L(0); PG8_BAR; PG8_MMA(1, 0, At, B0); PG8_MMA(1, 1, At, B1); PG8_BAR; PG8_SCHED;
;         }
;         if (wr == 0) PG8_BAR;
.Lgt_l_3_done:
	s_barrier
	s_add_i32 s69, s69, 2
	s_add_u32 s42, s42, 0x100
	s_addc_u32 s43, s43, 0
	s_add_u32 s52, s52, 0x100
	s_addc_u32 s53, s53, 0
	s_cmp_gt_u32 s69, 13
	s_cbranch_scc0 .LBB0_96
	s_and_b64 vcc, exec, s[18:19]
	s_cbranch_vccz .LBB0_99
	s_barrier

; #define PG8_STAGE(bufoff, gbase, voff) do { _Pragma("unroll") for (int _i = 0; _i < 2; ++_i) \
;         __builtin_amdgcn_global_load_lds((const unsigned*)((const char*)(gbase) + (voff)[_i]), (LAS unsigned*)(lds + (bufoff) + ldsw + _i * 8192), 16, 0, 0); } while (0)
; #define PG8_LDA(dst, b, h) do { _Pragma("unroll") for (int m = 0; m < 4; ++m) _Pragma("unroll") for (int k = 0; k < 2; ++k) dst[m][k] = *(const LAS bf16x8*)(lds + PG8_SA(b, h) + aoff + m * 2048 + k * 1024); } while (0)
; #define PG8_MMA(ai, bj, At, Bt) do { __builtin_amdgcn_s_setprio(1); _Pragma("unroll") for (int m = 0; m < 4; ++m) _Pragma("unroll") for (int n = 0; n < 2; ++n) _Pragma("unroll") for (int k = 0; k < 2; ++k) \
;         acc[ai][bj][m][n] = __builtin_amdgcn_mfma_f32_16x16x32_bf16(Bt[n][k], At[m][k], acc[ai][bj][m][n], 0, 0, 0); __builtin_amdgcn_s_setprio(0); } while (0)
; #define PG8_WAIT_V(n) asm volatile("s_waitcnt vmcnt(" #n ")" ::: "memory")
; #define PG8_WAIT_L(n) asm volatile("s_waitcnt lgkmcnt(" #n ")" ::: "memory")
; #define PG8_BAR __builtin_amdgcn_s_barrier()
; #define PG8_SCHED __builtin_amdgcn_sched_barrier(0)
;     __device__ __forceinline__ void operator()(const f32x4 (&acc)[2][2][4][2], const Unit& u, int wr, int wc, int fr, int fq, LAS unsigned char* lds, int tid, State& st) const {
;     ...
;         const bool gate = (u.pn == 12) && (wc == 0);
; template <class Epi, class Sched>
; __device__ __forceinline__ void gemm_phase(LAS unsigned char* lds, const Gemm g, const Sched& S, const Epi& E) {
;     ...
;             PG8_WAIT_V(8); PG8_WAIT_L(0); PG8_BAR; PG8_MMA(0, 0, At, B0); PG8_MMA(0, 1, At, B1); PG8_BAR; PG8_SCHED;
;             PG8_LDA(At, 0, 1); PG8_STAGE(PG8_SB(0, 0), b2, voffB); PG8_STAGE(PG8_SB(0, 1), b2 + hstepB, voffB); PG8_STAGE(PG8_SA(0, 0), a2, voffA);
;             PG8_WAIT_V(8); PG8_WAIT_L(0); PG8_BAR; PG8_MMA(1, 0, At, B0); PG8_MMA(1, 1, At, B1); PG8_BAR; PG8_SCHED;
.Lgt_l_0:
	s_cmp_lg_u32 s100, 0
	s_cbranch_scc1 .Lgt_l_0_done
	v_mfma_f32_16x16x32_bf16 v[128:131], v[144:147], v[204:207], v[128:131]
	v_mfma_f32_16x16x32_bf16 v[124:127], v[164:167], v[204:207], v[124:127]
	v_mfma_f32_16x16x32_bf16 v[120:123], v[144:147], v[212:215], v[120:123]
	v_mfma_f32_16x16x32_bf16 v[108:111], v[164:167], v[212:215], v[108:111]
	v_mfma_f32_16x16x32_bf16 v[104:107], v[144:147], v[220:223], v[104:107]
	v_mfma_f32_16x16x32_bf16 v[92:95], v[164:167], v[220:223], v[92:95]
	v_mfma_f32_16x16x32_bf16 v[88:91], v[144:147], v[228:231], v[88:91]
	v_mfma_f32_16x16x32_bf16 v[76:79], v[164:167], v[228:231], v[76:79]
	v_mfma_f32_16x16x32_bf16 v[128:131], v[148:151], v[208:211], v[128:131]
	v_mfma_f32_16x16x32_bf16 v[124:127], v[168:171], v[208:211], v[124:127]
	v_mfma_f32_16x16x32_bf16 v[120:123], v[148:151], v[216:219], v[120:123]
	v_mfma_f32_16x16x32_bf16 v[108:111], v[168:171], v[216:219], v[108:111]
	v_mfma_f32_16x16x32_bf16 v[104:107], v[148:151], v[224:227], v[104:107]
	v_mfma_f32_16x16x32_bf16 v[92:95], v[168:171], v[224:227], v[92:95]
	v_mfma_f32_16x16x32_bf16 v[88:91], v[148:151], v[232:235], v[88:91]
	v_mfma_f32_16x16x32_bf16 v[76:79], v[168:171], v[232:235], v[76:79]
	s_branch .Lgt_l_0_done
.Lgt_l_1:
	s_cmp_lg_u32 s100, 0
	s_cbranch_scc1 .Lgt_l_1_done
	v_mfma_f32_16x16x32_bf16 v[64:67], v[144:147], v[204:207], v[64:67]
	v_mfma_f32_16x16x32_bf16 v[60:63], v[164:167], v[204:207], v[60:63]
	v_mfma_f32_16x16x32_bf16 v[56:59], v[144:147], v[212:215], v[56:59]
	v_mfma_f32_16x16x32_bf16 v[44:47], v[164:167], v[212:215], v[44:47]
	v_mfma_f32_16x16x32_bf16 v[40:43], v[144:147], v[220:223], v[40:43]
	v_mfma_f32_16x16x32_bf16 v[28:31], v[164:167], v[220:223], v[28:31]
	v_mfma_f32_16x16x32_bf16 v[24:27], v[144:147], v[228:231], v[24:27]
	v_mfma_f32_16x16x32_bf16 v[12:15], v[164:167], v[228:231], v[12:15]
	v_mfma_f32_16x16x32_bf16 v[64:67], v[148:151], v[208:211], v[64:67]
	v_mfma_f32_16x16x32_bf16 v[60:63], v[168:171], v[208:211], v[60:63]
	v_mfma_f32_16x16x32_bf16 v[56:59], v[148:151], v[216:219], v[56:59]
	v_mfma_f32_16x16x32_bf16 v[44:47], v[168:171], v[216:219], v[44:47]
	v_mfma_f32_16x16x32_bf16 v[40:43], v[148:151], v[224:227], v[40:43]
	v_mfma_f32_16x16x32_bf16 v[28:31], v[168:171], v[224:227], v[28:31]
	v_mfma_f32_16x16x32_bf16 v[24:27], v[148:151], v[232:235], v[24:27]
	v_mfma_f32_16x16x32_bf16 v[12:15], v[168:171], v[232:235], v[12:15]
	s_branch .Lgt_l_1_done

; #define PG8_STAGE(bufoff, gbase, voff) do { _Pragma("unroll") for (int _i = 0; _i < 2; ++_i) \
;         __builtin_amdgcn_global_load_lds((const unsigned*)((const char*)(gbase) + (voff)[_i]), (LAS unsigned*)(lds + (bufoff) + ldsw + _i * 8192), 16, 0, 0); } while (0)
; #define PG8_LDA(dst, b, h) do { _Pragma("unroll") for (int m = 0; m < 4; ++m) _Pragma("unroll") for (int k = 0; k < 2; ++k) dst[m][k] = *(const LAS bf16x8*)(lds + PG8_SA(b, h) + aoff + m * 2048 + k * 1024); } while (0)
; #define PG8_MMA(ai, bj, At, Bt) do { __builtin_amdgcn_s_setprio(1); _Pragma("unroll") for (int m = 0; m < 4; ++m) _Pragma("unroll") for (int n = 0; n < 2; ++n) _Pragma("unroll") for (int k = 0; k < 2; ++k) \
;         acc[ai][bj][m][n] = __builtin_amdgcn_mfma_f32_16x16x32_bf16(Bt[n][k], At[m][k], acc[ai][bj][m][n], 0, 0, 0); __builtin_amdgcn_s_setprio(0); } while (0)
; #define PG8_WAIT_V(n) asm volatile("s_waitcnt vmcnt(" #n ")" ::: "memory")
; #define PG8_WAIT_L(n) asm volatile("s_waitcnt lgkmcnt(" #n ")" ::: "memory")
; #define PG8_BAR __builtin_amdgcn_s_barrier()
; #define PG8_SCHED __builtin_amdgcn_sched_barrier(0)
;     __device__ __forceinline__ void operator()(const f32x4 (&acc)[2][2][4][2], const Unit& u, int wr, int wc, int fr, int fq, LAS unsigned char* lds, int tid, State& st) const {
;     ...
;         const bool gate = (u.pn == 12) && (wc == 0);
; template <class Epi, class Sched>
; __device__ __forceinline__ void gemm_phase(LAS unsigned char* lds, const Gemm g, const Sched& S, const Epi& E) {
;     ...
;             PG8_WAIT_V(8); PG8_WAIT_L(0); PG8_BAR; PG8_MMA(0, 0, At, B0); PG8_MMA(0, 1, At, B1); PG8_BAR; PG8_SCHED;
;             PG8_LDA(At, 0, 1); PG8_STAGE(PG8_SB(0, 0), b2, voffB); PG8_STAGE(PG8_SB(0, 1), b2 + hstepB, voffB); PG8_STAGE(PG8_SA(0, 0), a2, voffA);
;             PG8_WAIT_V(8); PG8_WAIT_L(0); PG8_BAR; PG8_MMA(1, 0, At, B0); PG8_MMA(1, 1, At, B1); PG8_BAR; PG8_SCHED;
.Lgt_p_0:
	s_cmp_lg_u32 s100, 0
	s_cbranch_scc1 .Lgt_p_0_done
	v_mfma_f32_16x16x32_bf16 v[128:131], v[144:147], v[204:207], 0
	v_mfma_f32_16x16x32_bf16 v[124:127], v[164:167], v[204:207], 0
	v_mfma_f32_16x16x32_bf16 v[120:123], v[144:147], v[212:215], 0
	v_mfma_f32_16x16x32_bf16 v[108:111], v[164:167], v[212:215], 0
	v_mfma_f32_16x16x32_bf16 v[104:107], v[144:147], v[220:223], 0
	v_mfma_f32_16x16x32_bf16 v[92:95], v[164:167], v[220:223], 0
	v_mfma_f32_16x16x32_bf16 v[88:91], v[144:147], v[228:231], 0
	v_mfma_f32_16x16x32_bf16 v[76:79], v[164:167], v[228:231], 0
	v_mfma_f32_16x16x32_bf16 v[128:131], v[148:151], v[208:211], v[128:131]
	v_mfma_f32_16x16x32_bf16 v[124:127], v[168:171], v[208:211], v[124:127]
	v_mfma_f32_16x16x32_bf16 v[120:123], v[148:151], v[216:219], v[120:123]
	v_mfma_f32_16x16x32_bf16 v[108:111], v[168:171], v[216:219], v[108:111]
	v_mfma_f32_16x16x32_bf16 v[104:107], v[148:151], v[224:227], v[104:107]
	v_mfma_f32_16x16x32_bf16 v[92:95], v[168:171], v[224:227], v[92:95]
	v_mfma_f32_16x16x32_bf16 v[88:91], v[148:151], v[232:235], v[88:91]
	v_mfma_f32_16x16x32_bf16 v[76:79], v[168:171], v[232:235], v[76:79]
	s_branch .Lgt_p_0_done
.Lgt_p_1:
	s_cmp_lg_u32 s100, 0
	s_cbranch_scc1 .Lgt_p_1_done
	v_mfma_f32_16x16x32_bf16 v[64:67], v[144:147], v[204:207], 0
	v_mfma_f32_16x16x32_bf16 v[60:63], v[164:167], v[204:207], 0
	v_mfma_f32_16x16x32_bf16 v[56:59], v[144:147], v[212:215], 0
	v_mfma_f32_16x16x32_bf16 v[44:47], v[164:167], v[212:215], 0
	v_mfma_f32_16x16x32_bf16 v[40:43], v[144:147], v[220:223], 0
	v_mfma_f32_16x16x32_bf16 v[28:31], v[164:167], v[220:223], 0
	v_mfma_f32_16x16x32_bf16 v[24:27], v[144:147], v[228:231], 0
	v_mfma_f32_16x16x32_bf16 v[12:15], v[164:167], v[228:231], 0
	v_mfma_f32_16x16x32_bf16 v[64:67], v[148:151], v[208:211], v[64:67]
	v_mfma_f32_16x16x32_bf16 v[60:63], v[168:171], v[208:211], v[60:63]
	v_mfma_f32_16x16x32_bf16 v[56:59], v[148:151], v[216:219], v[56:59]
	v_mfma_f32_16x16x32_bf16 v[44:47], v[168:171], v[216:219], v[44:47]
	v_mfma_f32_16x16x32_bf16 v[40:43], v[148:151], v[224:227], v[40:43]
	v_mfma_f32_16x16x32_bf16 v[28:31], v[168:171], v[224:227], v[28:31]
	v_mfma_f32_16x16x32_bf16 v[24:27], v[148:151], v[232:235], v[24:27]
	v_mfma_f32_16x16x32_bf16 v[12:15], v[168:171], v[232:235], v[12:15]
	s_branch .Lgt_p_1_done

; __global__ void __launch_bounds__(NTHREADS, 2) fwd_megakernel(Params p) {
	.amdhsa_kernel _Z14fwd_megakernel6Params
		.amdhsa_group_segment_fixed_size 0
		.amdhsa_private_segment_fixed_size 0
		.amdhsa_kernarg_size 384
		.amdhsa_user_sgpr_count 2
		.amdhsa_user_sgpr_dispatch_ptr 0
		.amdhsa_user_sgpr_queue_ptr 0
		.amdhsa_user_sgpr_kernarg_segment_ptr 1
		.amdhsa_user_sgpr_dispatch_id 0
		.amdhsa_user_sgpr_kernarg_preload_length 0
		.amdhsa_user_sgpr_kernarg_preload_offset 0
		.amdhsa_user_sgpr_private_segment_size 0
		.amdhsa_uses_dynamic_stack 0
		.amdhsa_enable_private_segment 0
		.amdhsa_system_sgpr_workgroup_id_x 1
		.amdhsa_system_sgpr_workgroup_id_y 0
		.amdhsa_system_sgpr_workgroup_id_z 0
		.amdhsa_system_sgpr_workgroup_info 0
		.amdhsa_system_vgpr_workitem_id 2
		.amdhsa_next_free_vgpr 254
		.amdhsa_next_free_sgpr 102
		.amdhsa_accum_offset 256
		.amdhsa_reserve_vcc 1
		.amdhsa_float_round_mode_32 0
		.amdhsa_float_round_mode_16_64 0
		.amdhsa_float_denorm_mode_32 3
		.amdhsa_float_denorm_mode_16_64 3
		.amdhsa_dx10_clamp 1
		.amdhsa_ieee_mode 1
		.amdhsa_fp16_overflow 0
		.amdhsa_tg_split 0
		.amdhsa_exception_fp_ieee_invalid_op 0
		.amdhsa_exception_fp_denorm_src 0
		.amdhsa_exception_fp_ieee_div_zero 0
		.amdhsa_exception_fp_ieee_overflow 0
		.amdhsa_exception_fp_ieee_underflow 0
		.amdhsa_exception_fp_ieee_inexact 0
		.amdhsa_exception_int_div_zero 0
	.end_amdhsa_kernel

; __global__ void __launch_bounds__(NTHREADS, 2) fwd_megakernel(Params p) {
amdhsa.kernels:
  - .agpr_count:     0
    .args:
      - .offset:         0
        .size:           128
        .value_kind:     by_value
      - .offset:         128
        .size:           4
        .value_kind:     hidden_block_count_x
      - .offset:         132
        .size:           4
        .value_kind:     hidden_block_count_y
      - .offset:         136
        .size:           4
        .value_kind:     hidden_block_count_z
      - .offset:         140
        .size:           2
        .value_kind:     hidden_group_size_x
      - .offset:         142
        .size:           2
        .value_kind:     hidden_group_size_y
      - .offset:         144
        .size:           2
        .value_kind:     hidden_group_size_z
      - .offset:         146
        .size:           2
        .value_kind:     hidden_remainder_x
      - .offset:         148
        .size:           2
        .value_kind:     hidden_remainder_y
      - .offset:         150
        .size:           2
        .value_kind:     hidden_remainder_z
      - .offset:         168
        .size:           8
        .value_kind:     hidden_global_offset_x
      - .offset:         176
        .size:           8
        .value_kind:     hidden_global_offset_y
      - .offset:         184
        .size:           8
        .value_kind:     hidden_global_offset_z
      - .offset:         192
        .size:           2
        .value_kind:     hidden_grid_dims
      - .offset:         216
        .size:           8
        .value_kind:     hidden_multigrid_sync_arg
      - .offset:         248
        .size:           4
        .value_kind:     hidden_dynamic_lds_size
    .group_segment_fixed_size: 0
    .kernarg_segment_align: 8
    .kernarg_segment_size: 384
    .language:       OpenCL C
    .language_version:
      - 2
      - 0
    .max_flat_workgroup_size: 512
    .name:           _Z14fwd_megakernel6Params
    .private_segment_fixed_size: 0
    .sgpr_count:     108
    .sgpr_spill_count: 146
    .symbol:         _Z14fwd_megakernel6Params.kd
    .uniform_work_group_size: 1
    .uses_dynamic_stack: false
    .vgpr_count:     254
    .vgpr_spill_count: 0
    .wavefront_size: 64
